# MLA: masked hand-scheduled tail loop handles the six tiles around the causal diagonal (replaces the compiler general loop for qb>=1)
# baseline (speedup 1.0000x reference)
.Lmf_tail:
	s_mov_b32 s18, s83
	s_mov_b32 s17, 3
	v_lshlrev_b32_e32 v241, 2, v219
	v_sub_u32_e32 v240, v198, v241
.Lmf_mloop:
	s_add_i32 s84, s18, 1
	s_lshl_b32 s84, s84, 6
	v_subrev_u32_e32 v241, s84, v240
	ds_read_b128 v[162:165], v216 offset:13312
	ds_read_b128 v[166:169], v216 offset:19968
	ds_read_b128 v[172:175], v216 offset:13344
	ds_read_b128 v[176:179], v216 offset:20000
	ds_read_b128 v[180:183], v216 offset:13376
	global_load_dwordx4 v[130:133], v235, s[14:15]
	global_load_dwordx4 v[134:137], v236, s[14:15]
	s_add_u32 s14, s14, 0x18000
	s_addc_u32 s15, s15, 0
	global_load_dwordx4 v[142:145], v237, s[12:13]
	s_add_u32 s12, s12, 0x80
	s_addc_u32 s13, s13, 0
	s_waitcnt lgkmcnt(4)
	v_mfma_f32_32x32x16_bf16 v[34:49], v[162:165], v[98:101], v[146:161]
	ds_read_b128 v[184:187], v216 offset:20032
	v_exp_f32_e32 v66, v66
	v_exp_f32_e32 v67, v67
	v_exp_f32_e32 v68, v68
	v_exp_f32_e32 v69, v69
	v_add_f32_e32 v171, v66, v171
	v_exp_f32_e32 v70, v70
	s_waitcnt lgkmcnt(4)
	v_mfma_f32_32x32x16_bf16 v[50:65], v[166:169], v[98:101], v[146:161]
	ds_read_b128 v[188:191], v216 offset:13408
	v_exp_f32_e32 v71, v71
	v_add_f32_e32 v171, v68, v171
	v_exp_f32_e32 v72, v72
	v_add_f32_e32 v197, v67, v69
	v_exp_f32_e32 v73, v73
	v_add_f32_e32 v171, v70, v171
	s_waitcnt lgkmcnt(4)
	v_mfma_f32_32x32x16_bf16 v[34:49], v[172:175], v[102:105], v[34:49]
	ds_read_b128 v[192:195], v216 offset:20064
	v_add_f32_e32 v197, v71, v197
	v_cvt_pk_bf16_f32 v66, v66, v67
	v_add_f32_e32 v171, v72, v171
	v_cvt_pk_bf16_f32 v67, v68, v69
	v_add_f32_e32 v197, v73, v197
	v_cvt_pk_bf16_f32 v68, v70, v71
	v_cvt_pk_bf16_f32 v69, v72, v73
	v_exp_f32_e32 v74, v74
	v_exp_f32_e32 v75, v75
	s_waitcnt lgkmcnt(4)
	v_mfma_f32_32x32x16_bf16 v[50:65], v[176:179], v[102:105], v[50:65]
	ds_read_b128 v[162:165], v216 offset:13440
	v_exp_f32_e32 v76, v76
	v_exp_f32_e32 v77, v77
	v_add_f32_e32 v171, v74, v171
	v_exp_f32_e32 v78, v78
	v_add_f32_e32 v197, v75, v197
	v_exp_f32_e32 v79, v79
	s_waitcnt lgkmcnt(4)
	v_mfma_f32_32x32x16_bf16 v[34:49], v[180:183], v[106:109], v[34:49]
	ds_read_b128 v[166:169], v216 offset:20096
	v_add_f32_e32 v171, v76, v171
	v_exp_f32_e32 v80, v80
	v_add_f32_e32 v197, v77, v197
	v_exp_f32_e32 v81, v81
	v_add_f32_e32 v171, v78, v171
	v_add_f32_e32 v197, v79, v197
	s_waitcnt lgkmcnt(4)
	v_mfma_f32_32x32x16_bf16 v[50:65], v[184:187], v[106:109], v[50:65]
	ds_read_b128 v[172:175], v216 offset:13472
	v_cvt_pk_bf16_f32 v74, v74, v75
	v_add_f32_e32 v171, v80, v171
	v_cvt_pk_bf16_f32 v75, v76, v77
	v_add_f32_e32 v197, v81, v197
	v_cvt_pk_bf16_f32 v76, v78, v79
	v_cvt_pk_bf16_f32 v77, v80, v81
	v_exp_f32_e32 v82, v82
	v_exp_f32_e32 v83, v83
	s_waitcnt lgkmcnt(4)
	v_mfma_f32_32x32x16_bf16 v[34:49], v[188:191], v[110:113], v[34:49]
	ds_read_b128 v[176:179], v216 offset:20128
	v_exp_f32_e32 v84, v84
	v_exp_f32_e32 v85, v85
	v_add_f32_e32 v171, v82, v171
	v_exp_f32_e32 v86, v86
	v_add_f32_e32 v197, v83, v197
	v_exp_f32_e32 v87, v87
	s_waitcnt lgkmcnt(4)
	v_mfma_f32_32x32x16_bf16 v[50:65], v[192:195], v[110:113], v[50:65]
	ds_read_b128 v[180:183], v217 offset:26624
	v_add_f32_e32 v171, v84, v171
	v_exp_f32_e32 v88, v88
	v_add_f32_e32 v197, v85, v197
	v_exp_f32_e32 v89, v89
	v_add_f32_e32 v171, v86, v171
	v_add_f32_e32 v197, v87, v197
	v_cvt_pk_bf16_f32 v82, v82, v83
	v_add_f32_e32 v171, v88, v171
	s_waitcnt lgkmcnt(4)
	v_mfma_f32_32x32x16_bf16 v[34:49], v[162:165], v[114:117], v[34:49]
	ds_read_b128 v[184:187], v217 offset:31232
	v_cvt_pk_bf16_f32 v83, v84, v85
	v_add_f32_e32 v197, v89, v197
	v_cvt_pk_bf16_f32 v84, v86, v87
	v_cvt_pk_bf16_f32 v85, v88, v89
	v_exp_f32_e32 v90, v90
	v_exp_f32_e32 v91, v91
	v_exp_f32_e32 v92, v92
	s_waitcnt lgkmcnt(4)
	v_mfma_f32_32x32x16_bf16 v[50:65], v[166:169], v[114:117], v[50:65]
	ds_read_b128 v[188:191], v217 offset:26656
	v_exp_f32_e32 v93, v93
	v_add_f32_e32 v171, v90, v171
	v_exp_f32_e32 v94, v94
	v_add_f32_e32 v197, v91, v197
	v_exp_f32_e32 v95, v95
	v_add_f32_e32 v171, v92, v171
	s_waitcnt lgkmcnt(4)
	v_mfma_f32_32x32x16_bf16 v[34:49], v[172:175], v[118:121], v[34:49]
	ds_read_b128 v[192:195], v217 offset:31264
	v_exp_f32_e32 v96, v96
	v_add_f32_e32 v197, v93, v197
	v_exp_f32_e32 v97, v97
	v_add_f32_e32 v171, v94, v171
	v_add_f32_e32 v197, v95, v197
	v_cvt_pk_bf16_f32 v90, v90, v91
	v_add_f32_e32 v171, v96, v171
	v_cvt_pk_bf16_f32 v91, v92, v93
	s_waitcnt lgkmcnt(4)
	v_mfma_f32_32x32x16_bf16 v[50:65], v[176:179], v[118:121], v[50:65]
	ds_read_b128 v[162:165], v217 offset:26688
	v_add_f32_e32 v197, v97, v197
	v_cvt_pk_bf16_f32 v92, v94, v95
	v_cvt_pk_bf16_f32 v93, v96, v97
	s_waitcnt lgkmcnt(4)
	v_mfma_f32_32x32x16_bf16 v[18:33], v[180:183], v[66:69], v[18:33]
	ds_read_b128 v[166:169], v217 offset:31296
	s_waitcnt lgkmcnt(4)
	v_mfma_f32_32x32x16_bf16 v[2:17], v[184:187], v[66:69], v[2:17]
	ds_read_b128 v[172:175], v217 offset:26720
	v_cmp_gt_i32_e64 vcc, 0, v241
	v_cmp_gt_i32_e64 s[42:43], 1, v241
	v_cmp_gt_i32_e64 s[44:45], 2, v241
	v_cmp_gt_i32_e64 s[46:47], 3, v241
	v_cmp_gt_i32_e64 s[48:49], 8, v241
	v_cmp_gt_i32_e64 s[50:51], 9, v241
	v_cndmask_b32_e64 v34, v34, v213, vcc
	v_cndmask_b32_e64 v35, v35, v213, s[42:43]
	v_cndmask_b32_e64 v36, v36, v213, s[44:45]
	v_cndmask_b32_e64 v37, v37, v213, s[46:47]
	v_cndmask_b32_e64 v38, v38, v213, s[48:49]
	v_cndmask_b32_e64 v39, v39, v213, s[50:51]
	v_cmp_gt_i32_e64 vcc, 10, v241
	v_cmp_gt_i32_e64 s[42:43], 11, v241
	v_cmp_gt_i32_e64 s[44:45], 16, v241
	v_cmp_gt_i32_e64 s[46:47], 17, v241
	v_cmp_gt_i32_e64 s[48:49], 18, v241
	v_cmp_gt_i32_e64 s[50:51], 19, v241
	v_cndmask_b32_e64 v40, v40, v213, vcc
	v_cndmask_b32_e64 v41, v41, v213, s[42:43]
	v_cndmask_b32_e64 v42, v42, v213, s[44:45]
	v_cndmask_b32_e64 v43, v43, v213, s[46:47]
	v_cndmask_b32_e64 v44, v44, v213, s[48:49]
	v_cndmask_b32_e64 v45, v45, v213, s[50:51]
	v_cmp_gt_i32_e64 vcc, 24, v241
	v_cmp_gt_i32_e64 s[42:43], 25, v241
	v_cmp_gt_i32_e64 s[44:45], 26, v241
	s_waitcnt lgkmcnt(4)
	v_mfma_f32_32x32x16_bf16 v[18:33], v[188:191], v[74:77], v[18:33]
	ds_read_b128 v[176:179], v217 offset:31328
	v_cmp_gt_i32_e64 s[46:47], 27, v241
	v_cmp_gt_i32_e64 s[48:49], 32, v241
	v_cmp_gt_i32_e64 s[50:51], 33, v241
	v_cndmask_b32_e64 v46, v46, v213, vcc
	v_cndmask_b32_e64 v47, v47, v213, s[42:43]
	v_cndmask_b32_e64 v48, v48, v213, s[44:45]
	v_cndmask_b32_e64 v49, v49, v213, s[46:47]
	v_cndmask_b32_e64 v50, v50, v213, s[48:49]
	v_cndmask_b32_e64 v51, v51, v213, s[50:51]
	s_waitcnt lgkmcnt(4)
	v_mfma_f32_32x32x16_bf16 v[2:17], v[192:195], v[74:77], v[2:17]
	s_waitcnt vmcnt(3)
	v_add_u32_e32 v196, 0x8800, v215
	ds_write_b128 v228, v[122:125]
	ds_write_b128 v238, v[126:129]
	ds_write2_b64 v196, v[138:139], v[140:141] offset0:128 offset1:130
	v_cmp_gt_i32_e64 vcc, 34, v241
	v_cmp_gt_i32_e64 s[42:43], 35, v241
	v_cmp_gt_i32_e64 s[44:45], 40, v241
	v_cmp_gt_i32_e64 s[46:47], 41, v241
	v_cmp_gt_i32_e64 s[48:49], 42, v241
	v_cmp_gt_i32_e64 s[50:51], 43, v241
	v_cndmask_b32_e64 v52, v52, v213, vcc
	v_cndmask_b32_e64 v53, v53, v213, s[42:43]
	v_cndmask_b32_e64 v54, v54, v213, s[44:45]
	v_cndmask_b32_e64 v55, v55, v213, s[46:47]
	s_waitcnt lgkmcnt(6)
	v_mfma_f32_32x32x16_bf16 v[18:33], v[162:165], v[82:85], v[18:33]
	v_cndmask_b32_e64 v56, v56, v213, s[48:49]
	v_cndmask_b32_e64 v57, v57, v213, s[50:51]
	v_cmp_gt_i32_e64 vcc, 48, v241
	v_cmp_gt_i32_e64 s[42:43], 49, v241
	v_cmp_gt_i32_e64 s[44:45], 50, v241
	v_cmp_gt_i32_e64 s[46:47], 51, v241
	v_cmp_gt_i32_e64 s[48:49], 56, v241
	v_cmp_gt_i32_e64 s[50:51], 57, v241
	v_cndmask_b32_e64 v58, v58, v213, vcc
	v_cndmask_b32_e64 v59, v59, v213, s[42:43]
	s_waitcnt lgkmcnt(5)
	v_mfma_f32_32x32x16_bf16 v[2:17], v[166:169], v[82:85], v[2:17]
	v_cndmask_b32_e64 v60, v60, v213, s[44:45]
	v_cndmask_b32_e64 v61, v61, v213, s[46:47]
	v_cndmask_b32_e64 v62, v62, v213, s[48:49]
	v_cndmask_b32_e64 v63, v63, v213, s[50:51]
	v_cmp_gt_i32_e64 vcc, 58, v241
	v_cmp_gt_i32_e64 s[42:43], 59, v241
	s_nop 1
	v_cndmask_b32_e64 v64, v64, v213, vcc
	v_cndmask_b32_e64 v65, v65, v213, s[42:43]
	v_max3_f32 v1, v34, v35, v36
	s_waitcnt lgkmcnt(4)
	v_mfma_f32_32x32x16_bf16 v[18:33], v[172:175], v[90:93], v[18:33]
	v_max3_f32 v170, v37, v38, v39
	v_max3_f32 v1, v1, v40, v41
	v_max3_f32 v170, v170, v42, v43
	v_max3_f32 v1, v1, v44, v45
	v_max3_f32 v170, v170, v46, v47
	v_max3_f32 v1, v1, v48, v49
	v_max3_f32 v170, v170, v50, v51
	v_max3_f32 v1, v1, v52, v53
	v_max3_f32 v170, v170, v54, v55
	v_max3_f32 v1, v1, v56, v57
	s_waitcnt lgkmcnt(3)
	v_mfma_f32_32x32x16_bf16 v[2:17], v[176:179], v[90:93], v[2:17]
	v_max3_f32 v170, v170, v58, v59
	v_max3_f32 v1, v1, v60, v61
	v_max3_f32 v170, v170, v62, v63
	v_max3_f32 v1, v1, v64, v65
	v_max_f32_e32 v1, v1, v170
	v_mov_b32_e32 v170, v1
	v_add_f32_e32 v171, v197, v171
	s_nop 0
	v_permlane32_swap_b32_e32 v1, v170
	v_max_f32_e32 v1, v1, v170
	v_cmp_lt_f32_e32 vcc, s93, v1
	s_cbranch_vccnz .Lmf_slow_m0
.Lmf_join_m0:
	s_waitcnt lgkmcnt(0)
	s_barrier
	s_add_i32 s84, s18, 2
	s_lshl_b32 s84, s84, 6
	v_subrev_u32_e32 v241, s84, v240
	ds_read_b128 v[162:165], v216 offset:0
	ds_read_b128 v[166:169], v216 offset:6656
	ds_read_b128 v[172:175], v216 offset:32
	ds_read_b128 v[176:179], v216 offset:6688
	ds_read_b128 v[180:183], v216 offset:64
	global_load_dwordx4 v[122:125], v235, s[14:15]
	global_load_dwordx4 v[126:129], v236, s[14:15]
	s_add_u32 s14, s14, 0x18000
	s_addc_u32 s15, s15, 0
	global_load_dwordx4 v[138:141], v237, s[12:13]
	s_add_u32 s12, s12, 0x80
	s_addc_u32 s13, s13, 0
	s_waitcnt lgkmcnt(4)
	v_mfma_f32_32x32x16_bf16 v[66:81], v[162:165], v[98:101], v[146:161]
	ds_read_b128 v[184:187], v216 offset:6720
	v_exp_f32_e32 v34, v34
	v_exp_f32_e32 v35, v35
	v_exp_f32_e32 v36, v36
	v_exp_f32_e32 v37, v37
	v_add_f32_e32 v171, v34, v171
	v_exp_f32_e32 v38, v38
	s_waitcnt lgkmcnt(4)
	v_mfma_f32_32x32x16_bf16 v[82:97], v[166:169], v[98:101], v[146:161]
	ds_read_b128 v[188:191], v216 offset:96
	v_exp_f32_e32 v39, v39
	v_add_f32_e32 v171, v36, v171
	v_exp_f32_e32 v40, v40
	v_add_f32_e32 v197, v35, v37
	v_exp_f32_e32 v41, v41
	v_add_f32_e32 v171, v38, v171
	s_waitcnt lgkmcnt(4)
	v_mfma_f32_32x32x16_bf16 v[66:81], v[172:175], v[102:105], v[66:81]
	ds_read_b128 v[192:195], v216 offset:6752
	v_add_f32_e32 v197, v39, v197
	v_cvt_pk_bf16_f32 v34, v34, v35
	v_add_f32_e32 v171, v40, v171
	v_cvt_pk_bf16_f32 v35, v36, v37
	v_add_f32_e32 v197, v41, v197
	v_cvt_pk_bf16_f32 v36, v38, v39
	v_cvt_pk_bf16_f32 v37, v40, v41
	v_exp_f32_e32 v42, v42
	v_exp_f32_e32 v43, v43
	s_waitcnt lgkmcnt(4)
	v_mfma_f32_32x32x16_bf16 v[82:97], v[176:179], v[102:105], v[82:97]
	ds_read_b128 v[162:165], v216 offset:128
	v_exp_f32_e32 v44, v44
	v_exp_f32_e32 v45, v45
	v_add_f32_e32 v171, v42, v171
	v_exp_f32_e32 v46, v46
	v_add_f32_e32 v197, v43, v197
	v_exp_f32_e32 v47, v47
	s_waitcnt lgkmcnt(4)
	v_mfma_f32_32x32x16_bf16 v[66:81], v[180:183], v[106:109], v[66:81]
	ds_read_b128 v[166:169], v216 offset:6784
	v_add_f32_e32 v171, v44, v171
	v_exp_f32_e32 v48, v48
	v_add_f32_e32 v197, v45, v197
	v_exp_f32_e32 v49, v49
	v_add_f32_e32 v171, v46, v171
	v_add_f32_e32 v197, v47, v197
	s_waitcnt lgkmcnt(4)
	v_mfma_f32_32x32x16_bf16 v[82:97], v[184:187], v[106:109], v[82:97]
	ds_read_b128 v[172:175], v216 offset:160
	v_cvt_pk_bf16_f32 v42, v42, v43
	v_add_f32_e32 v171, v48, v171
	v_cvt_pk_bf16_f32 v43, v44, v45
	v_add_f32_e32 v197, v49, v197
	v_cvt_pk_bf16_f32 v44, v46, v47
	v_cvt_pk_bf16_f32 v45, v48, v49
	v_exp_f32_e32 v50, v50
	v_exp_f32_e32 v51, v51
	s_waitcnt lgkmcnt(4)
	v_mfma_f32_32x32x16_bf16 v[66:81], v[188:191], v[110:113], v[66:81]
	ds_read_b128 v[176:179], v216 offset:6816
	v_exp_f32_e32 v52, v52
	v_exp_f32_e32 v53, v53
	v_add_f32_e32 v171, v50, v171
	v_exp_f32_e32 v54, v54
	v_add_f32_e32 v197, v51, v197
	v_exp_f32_e32 v55, v55
	s_waitcnt lgkmcnt(4)
	v_mfma_f32_32x32x16_bf16 v[82:97], v[192:195], v[110:113], v[82:97]
	ds_read_b128 v[180:183], v217 offset:35840
	v_add_f32_e32 v171, v52, v171
	v_exp_f32_e32 v56, v56
	v_add_f32_e32 v197, v53, v197
	v_exp_f32_e32 v57, v57
	v_add_f32_e32 v171, v54, v171
	v_add_f32_e32 v197, v55, v197
	v_cvt_pk_bf16_f32 v50, v50, v51
	v_add_f32_e32 v171, v56, v171
	s_waitcnt lgkmcnt(4)
	v_mfma_f32_32x32x16_bf16 v[66:81], v[162:165], v[114:117], v[66:81]
	ds_read_b128 v[184:187], v217 offset:40448
	v_cvt_pk_bf16_f32 v51, v52, v53
	v_add_f32_e32 v197, v57, v197
	v_cvt_pk_bf16_f32 v52, v54, v55
	v_cvt_pk_bf16_f32 v53, v56, v57
	v_exp_f32_e32 v58, v58
	v_exp_f32_e32 v59, v59
	v_exp_f32_e32 v60, v60
	s_waitcnt lgkmcnt(4)
	v_mfma_f32_32x32x16_bf16 v[82:97], v[166:169], v[114:117], v[82:97]
	ds_read_b128 v[188:191], v217 offset:35872
	v_exp_f32_e32 v61, v61
	v_add_f32_e32 v171, v58, v171
	v_exp_f32_e32 v62, v62
	v_add_f32_e32 v197, v59, v197
	v_exp_f32_e32 v63, v63
	v_add_f32_e32 v171, v60, v171
	s_waitcnt lgkmcnt(4)
	v_mfma_f32_32x32x16_bf16 v[66:81], v[172:175], v[118:121], v[66:81]
	ds_read_b128 v[192:195], v217 offset:40480
	v_exp_f32_e32 v64, v64
	v_add_f32_e32 v197, v61, v197
	v_exp_f32_e32 v65, v65
	v_add_f32_e32 v171, v62, v171
	v_add_f32_e32 v197, v63, v197
	v_cvt_pk_bf16_f32 v58, v58, v59
	v_add_f32_e32 v171, v64, v171
	v_cvt_pk_bf16_f32 v59, v60, v61
	s_waitcnt lgkmcnt(4)
	v_mfma_f32_32x32x16_bf16 v[82:97], v[176:179], v[118:121], v[82:97]
	ds_read_b128 v[162:165], v217 offset:35904
	v_add_f32_e32 v197, v65, v197
	v_cvt_pk_bf16_f32 v60, v62, v63
	v_cvt_pk_bf16_f32 v61, v64, v65
	s_waitcnt lgkmcnt(4)
	v_mfma_f32_32x32x16_bf16 v[18:33], v[180:183], v[34:37], v[18:33]
	ds_read_b128 v[166:169], v217 offset:40512
	s_waitcnt lgkmcnt(4)
	v_mfma_f32_32x32x16_bf16 v[2:17], v[184:187], v[34:37], v[2:17]
	ds_read_b128 v[172:175], v217 offset:35936
	v_cmp_gt_i32_e64 vcc, 0, v241
	v_cmp_gt_i32_e64 s[42:43], 1, v241
	v_cmp_gt_i32_e64 s[44:45], 2, v241
	v_cmp_gt_i32_e64 s[46:47], 3, v241
	v_cmp_gt_i32_e64 s[48:49], 8, v241
	v_cmp_gt_i32_e64 s[50:51], 9, v241
	v_cndmask_b32_e64 v66, v66, v213, vcc
	v_cndmask_b32_e64 v67, v67, v213, s[42:43]
	v_cndmask_b32_e64 v68, v68, v213, s[44:45]
	v_cndmask_b32_e64 v69, v69, v213, s[46:47]
	v_cndmask_b32_e64 v70, v70, v213, s[48:49]
	v_cndmask_b32_e64 v71, v71, v213, s[50:51]
	v_cmp_gt_i32_e64 vcc, 10, v241
	v_cmp_gt_i32_e64 s[42:43], 11, v241
	v_cmp_gt_i32_e64 s[44:45], 16, v241
	v_cmp_gt_i32_e64 s[46:47], 17, v241
	v_cmp_gt_i32_e64 s[48:49], 18, v241
	v_cmp_gt_i32_e64 s[50:51], 19, v241
	v_cndmask_b32_e64 v72, v72, v213, vcc
	v_cndmask_b32_e64 v73, v73, v213, s[42:43]
	v_cndmask_b32_e64 v74, v74, v213, s[44:45]
	v_cndmask_b32_e64 v75, v75, v213, s[46:47]
	v_cndmask_b32_e64 v76, v76, v213, s[48:49]
	v_cndmask_b32_e64 v77, v77, v213, s[50:51]
	v_cmp_gt_i32_e64 vcc, 24, v241
	v_cmp_gt_i32_e64 s[42:43], 25, v241
	v_cmp_gt_i32_e64 s[44:45], 26, v241
	s_waitcnt lgkmcnt(4)
	v_mfma_f32_32x32x16_bf16 v[18:33], v[188:191], v[42:45], v[18:33]
	ds_read_b128 v[176:179], v217 offset:40544
	v_cmp_gt_i32_e64 s[46:47], 27, v241
	v_cmp_gt_i32_e64 s[48:49], 32, v241
	v_cmp_gt_i32_e64 s[50:51], 33, v241
	v_cndmask_b32_e64 v78, v78, v213, vcc
	v_cndmask_b32_e64 v79, v79, v213, s[42:43]
	v_cndmask_b32_e64 v80, v80, v213, s[44:45]
	v_cndmask_b32_e64 v81, v81, v213, s[46:47]
	v_cndmask_b32_e64 v82, v82, v213, s[48:49]
	v_cndmask_b32_e64 v83, v83, v213, s[50:51]
	s_waitcnt lgkmcnt(4)
	v_mfma_f32_32x32x16_bf16 v[2:17], v[192:195], v[42:45], v[2:17]
	s_waitcnt vmcnt(3)
	ds_write_b128 v228, v[130:133] offset:13312
	ds_write_b128 v238, v[134:137] offset:13312
	ds_write2_b64 v225, v[142:143], v[144:145] offset1:2
	v_cmp_gt_i32_e64 vcc, 34, v241
	v_cmp_gt_i32_e64 s[42:43], 35, v241
	v_cmp_gt_i32_e64 s[44:45], 40, v241
	v_cmp_gt_i32_e64 s[46:47], 41, v241
	v_cmp_gt_i32_e64 s[48:49], 42, v241
	v_cmp_gt_i32_e64 s[50:51], 43, v241
	v_cndmask_b32_e64 v84, v84, v213, vcc
	v_cndmask_b32_e64 v85, v85, v213, s[42:43]
	v_cndmask_b32_e64 v86, v86, v213, s[44:45]
	v_cndmask_b32_e64 v87, v87, v213, s[46:47]
	s_waitcnt lgkmcnt(6)
	v_mfma_f32_32x32x16_bf16 v[18:33], v[162:165], v[50:53], v[18:33]
	v_cndmask_b32_e64 v88, v88, v213, s[48:49]
	v_cndmask_b32_e64 v89, v89, v213, s[50:51]
	v_cmp_gt_i32_e64 vcc, 48, v241
	v_cmp_gt_i32_e64 s[42:43], 49, v241
	v_cmp_gt_i32_e64 s[44:45], 50, v241
	v_cmp_gt_i32_e64 s[46:47], 51, v241
	v_cmp_gt_i32_e64 s[48:49], 56, v241
	v_cmp_gt_i32_e64 s[50:51], 57, v241
	v_cndmask_b32_e64 v90, v90, v213, vcc
	v_cndmask_b32_e64 v91, v91, v213, s[42:43]
	s_waitcnt lgkmcnt(5)
	v_mfma_f32_32x32x16_bf16 v[2:17], v[166:169], v[50:53], v[2:17]
	v_cndmask_b32_e64 v92, v92, v213, s[44:45]
	v_cndmask_b32_e64 v93, v93, v213, s[46:47]
	v_cndmask_b32_e64 v94, v94, v213, s[48:49]
	v_cndmask_b32_e64 v95, v95, v213, s[50:51]
	v_cmp_gt_i32_e64 vcc, 58, v241
	v_cmp_gt_i32_e64 s[42:43], 59, v241
	s_nop 1
	v_cndmask_b32_e64 v96, v96, v213, vcc
	v_cndmask_b32_e64 v97, v97, v213, s[42:43]
	v_max3_f32 v1, v66, v67, v68
	s_waitcnt lgkmcnt(4)
	v_mfma_f32_32x32x16_bf16 v[18:33], v[172:175], v[58:61], v[18:33]
	v_max3_f32 v170, v69, v70, v71
	v_max3_f32 v1, v1, v72, v73
	v_max3_f32 v170, v170, v74, v75
	v_max3_f32 v1, v1, v76, v77
	v_max3_f32 v170, v170, v78, v79
	v_max3_f32 v1, v1, v80, v81
	v_max3_f32 v170, v170, v82, v83
	v_max3_f32 v1, v1, v84, v85
	v_max3_f32 v170, v170, v86, v87
	v_max3_f32 v1, v1, v88, v89
	s_waitcnt lgkmcnt(3)
	v_mfma_f32_32x32x16_bf16 v[2:17], v[176:179], v[58:61], v[2:17]
	v_max3_f32 v170, v170, v90, v91
	v_max3_f32 v1, v1, v92, v93
	v_max3_f32 v170, v170, v94, v95
	v_max3_f32 v1, v1, v96, v97
	v_max_f32_e32 v1, v1, v170
	v_mov_b32_e32 v170, v1
	v_add_f32_e32 v171, v197, v171
	s_nop 0
	v_permlane32_swap_b32_e32 v1, v170
	v_max_f32_e32 v1, v1, v170
	v_cmp_lt_f32_e32 vcc, s93, v1
	s_cbranch_vccnz .Lmf_slow_m1
.Lmf_join_m1:
	s_waitcnt lgkmcnt(0)
	s_barrier
	s_add_i32 s18, s18, 2
	s_add_i32 s17, s17, -1
	s_cmp_lg_u32 s17, 0
	s_cbranch_scc1 .Lmf_mloop
	s_mov_b32 s83, s18
	s_branch .Lmf_exit
